# attention vector segments: common no-rescale path falls through; rescale-factor computation, O-rescale blocks and the early-K drain moved out of line (4 taken branches and 5 instructions fewer per ite
# baseline (speedup 1.0000x reference)
; __device__ __forceinline__ void sel_mask_tile(f32x16& p0, f32x16& p1, unsigned wlo, unsigned whi, int hi) {
;     const unsigned NEGB = 0xff800000u;
;     const unsigned lo = wlo >> (4 * hi), h2 = whi >> (4 * hi);
; #pragma unroll
;     for (int r = 0; r < 16; ++r) {
;         const int c = (r & 3) + 8 * (r >> 2);
;         const unsigned m0 = (unsigned)__builtin_amdgcn_sbfe((int)lo, c, 1), m1 = (unsigned)__builtin_amdgcn_sbfe((int)h2, c, 1);
;         p0[r] = __uint_as_float((__float_as_uint(p0[r]) & m0) | (NEGB & ~m0));
;         p1[r] = __uint_as_float((__float_as_uint(p1[r]) & m1) | (NEGB & ~m1));
;     }
; }
; __device__ __forceinline__ void partialSM(f32x16& p0, f32x16& p1, float& m_reg, float& mn, float& alpha) {
;     float pmax = p0[0];
; #pragma unroll
;     for (int r = 1; r < 16; ++r) pmax = fmaxf(pmax, p0[r]);
; #pragma unroll
;     for (int r = 0; r < 16; ++r) pmax = fmaxf(pmax, p1[r]);
;     { auto rr = __builtin_amdgcn_permlane32_swap(__float_as_uint(pmax), __float_as_uint(pmax), false, false);
;       pmax = fmaxf(__uint_as_float(rr[0]), __uint_as_float(rr[1])); }
;     constexpr float C2 = 1.4426950408889634f * SCALE;
;     if (__builtin_expect(__all((pmax - m_reg) * SCALE <= THR), 1)) { mn = m_reg; alpha = 1.f; }
;     else { mn = fmaxf(m_reg, pmax); alpha = __builtin_amdgcn_exp2f((m_reg - mn) * C2); m_reg = mn; }
.Lp5_k2_done:
	s_nop 0
	s_waitcnt vmcnt(4)
	v_lshrrev_b32_e32 v160, v163, v146
	v_lshrrev_b32_e32 v161, v163, v147
	v_bfe_i32 v146, v160, 0, 1
	v_bfe_i32 v147, v161, 0, 1
	v_bitop3_b32 v146, v66, s74, v146 bitop3:0xe4
	v_bitop3_b32 v66, v82, s74, v147 bitop3:0xe4
	v_bfe_i32 v82, v160, 1, 1
	v_bfe_i32 v147, v161, 1, 1
	v_bitop3_b32 v82, v67, s74, v82 bitop3:0xe4
	v_bitop3_b32 v67, v83, s74, v147 bitop3:0xe4
	v_bfe_i32 v83, v160, 2, 1
	v_bfe_i32 v147, v161, 2, 1
	v_bitop3_b32 v83, v68, s74, v83 bitop3:0xe4
	v_bitop3_b32 v68, v84, s74, v147 bitop3:0xe4
	v_bfe_i32 v84, v160, 3, 1
	v_bfe_i32 v148, v161, 3, 1
	v_bitop3_b32 v147, v69, s74, v84 bitop3:0xe4
	v_bfe_i32 v84, v160, 8, 1
	v_bitop3_b32 v69, v85, s74, v148 bitop3:0xe4
	v_bfe_i32 v85, v161, 8, 1
	v_bitop3_b32 v148, v70, s74, v84 bitop3:0xe4
	v_bfe_i32 v84, v160, 9, 1
	v_bitop3_b32 v70, v86, s74, v85 bitop3:0xe4
	v_bfe_i32 v85, v161, 9, 1
	v_bitop3_b32 v149, v71, s74, v84 bitop3:0xe4
	v_bfe_i32 v84, v160, 10, 1
	v_bitop3_b32 v71, v87, s74, v85 bitop3:0xe4
	v_bfe_i32 v85, v161, 10, 1
	v_bitop3_b32 v87, v72, s74, v84 bitop3:0xe4
	v_bfe_i32 v84, v160, 11, 1
	v_bitop3_b32 v72, v88, s74, v85 bitop3:0xe4
	v_bfe_i32 v85, v161, 11, 1
	v_bitop3_b32 v88, v73, s74, v84 bitop3:0xe4
	v_bfe_i32 v73, v160, 16, 1
	v_bitop3_b32 v84, v89, s74, v85 bitop3:0xe4
	v_bfe_i32 v85, v161, 16, 1
	v_bitop3_b32 v89, v74, s74, v73 bitop3:0xe4
	v_bfe_i32 v73, v160, 17, 1
	v_bfe_i32 v74, v161, 17, 1
	v_bitop3_b32 v85, v90, s74, v85 bitop3:0xe4
	v_bitop3_b32 v90, v75, s74, v73 bitop3:0xe4
	v_bitop3_b32 v86, v91, s74, v74 bitop3:0xe4
	v_bfe_i32 v73, v160, 18, 1
	v_bfe_i32 v74, v161, 18, 1
	v_bitop3_b32 v91, v76, s74, v73 bitop3:0xe4
	v_bitop3_b32 v76, v92, s74, v74 bitop3:0xe4
	v_bfe_i32 v73, v160, 19, 1
	v_bfe_i32 v74, v161, 19, 1
	v_bitop3_b32 v92, v77, s74, v73 bitop3:0xe4
	v_bitop3_b32 v77, v93, s74, v74 bitop3:0xe4
	v_bfe_i32 v73, v160, 24, 1
	v_bfe_i32 v74, v161, 24, 1
	v_bitop3_b32 v93, v78, s74, v73 bitop3:0xe4
	v_bitop3_b32 v78, v94, s74, v74 bitop3:0xe4
	v_bfe_i32 v73, v160, 25, 1
	v_bfe_i32 v74, v161, 25, 1
	v_bitop3_b32 v79, v79, s74, v73 bitop3:0xe4
	v_bitop3_b32 v73, v95, s74, v74 bitop3:0xe4
	v_bfe_i32 v74, v160, 26, 1
	v_bfe_i32 v75, v161, 26, 1
	v_bitop3_b32 v80, v80, s74, v74 bitop3:0xe4
	v_bitop3_b32 v74, v96, s74, v75 bitop3:0xe4
	v_bfe_i32 v75, v160, 27, 1
	v_bfe_i32 v94, v161, 27, 1
	v_bitop3_b32 v81, v81, s74, v75 bitop3:0xe4
	v_bitop3_b32 v75, v97, s74, v94 bitop3:0xe4
	v_max_f32_e32 v94, v146, v82
	v_max3_f32 v94, v94, v83, v147
	v_max3_f32 v94, v94, v148, v149
	v_max3_f32 v94, v94, v87, v88
	v_max3_f32 v94, v94, v89, v90
	v_max3_f32 v94, v94, v91, v92
	v_max3_f32 v94, v94, v93, v79
	v_max3_f32 v94, v94, v80, v81
	v_max3_f32 v94, v94, v66, v67
	v_max3_f32 v94, v94, v68, v69
	v_max3_f32 v94, v94, v70, v71
	v_max3_f32 v94, v94, v72, v84
	v_max3_f32 v94, v94, v85, v86
	v_max3_f32 v94, v94, v76, v77
	v_max3_f32 v94, v94, v78, v73
	v_max3_f32 v94, v94, v74, v75
	v_mov_b32_e32 v95, v94
	s_nop 1
	v_permlane32_swap_b32_e32 v94, v95
	v_max_f32_e32 v94, v94, v95
	v_sub_f32_e32 v95, v94, v206
	v_mul_f32_e32 v95, 0x3db504f3, v95
	v_cmp_ge_f32_e32 vcc, s75, v95
	s_cmp_eq_u64 vcc, exec
	s_cselect_b64 s[6:7], -1, 0
	s_cbranch_scc0 .Lp5_y1_slow
	v_mov_b32_e32 v208, 1.0

; __device__ __forceinline__ void partialSM(f32x16& p0, f32x16& p1, float& m_reg, float& mn, float& alpha) {
;     ...
;     if (__builtin_expect(__all((pmax - m_reg) * SCALE <= THR), 1)) { mn = m_reg; alpha = 1.f; }
;     else { mn = fmaxf(m_reg, pmax); alpha = __builtin_amdgcn_exp2f((m_reg - mn) * C2); m_reg = mn; }
.LBB0_1307:
	v_mov_b32_e32 v207, 1.0
	s_cbranch_scc0 .Lp5_y2_slow

; __device__ __forceinline__ void partialSM(f32x16& p0, f32x16& p1, float& m_reg, float& mn, float& alpha) {
;     ...
;     if (__builtin_expect(__all((pmax - m_reg) * SCALE <= THR), 1)) { mn = m_reg; alpha = 1.f; }
;     else { mn = fmaxf(m_reg, pmax); alpha = __builtin_amdgcn_exp2f((m_reg - mn) * C2); m_reg = mn; }
;     const float mnL = -mn * C2;
.Lp5_y1_slow:
	v_max_f32_e32 v94, v206, v94
	v_sub_f32_e32 v96, v206, v94
	v_mul_f32_e32 v96, 0x3e0293ee, v96
	v_exp_f32_e32 v96, v96
	s_nop 0
	v_cndmask_b32_e64 v208, v96, 1.0, s[6:7]
	v_mov_b32_e32 v206, v94
	v_mul_f32_e32 v190, 0xbe0293ee, v94
	s_and_saveexec_b64 s[36:37], s[0:1]
	ds_write_b32 v185, v208 offset:128
	s_or_b64 exec, exec, s[36:37]
	s_waitcnt lgkmcnt(0)
	ds_read_b128 v[150:153], v183 offset:224
	ds_read_b128 v[154:157], v183 offset:192
	ds_read_b128 v[158:161], v183 offset:160
	ds_read_b128 v[172:175], v183 offset:128
	s_waitcnt lgkmcnt(3)
	v_pk_mul_f32 v[16:17], v[16:17], v[152:153]
	s_waitcnt lgkmcnt(2)
	v_pk_mul_f32 v[12:13], v[12:13], v[156:157]
	s_waitcnt lgkmcnt(1)
	v_pk_mul_f32 v[8:9], v[8:9], v[160:161]
	s_waitcnt lgkmcnt(0)
	v_pk_mul_f32 v[4:5], v[4:5], v[174:175]
	v_pk_mul_f32 v[14:15], v[14:15], v[150:151]
	v_pk_mul_f32 v[10:11], v[10:11], v[154:155]
	v_pk_mul_f32 v[6:7], v[6:7], v[158:159]
	v_pk_mul_f32 v[2:3], v[2:3], v[172:173]
	v_pk_mul_f32 v[64:65], v[64:65], v[152:153]
	v_pk_mul_f32 v[60:61], v[60:61], v[156:157]
	v_pk_mul_f32 v[56:57], v[56:57], v[160:161]
	v_pk_mul_f32 v[52:53], v[52:53], v[174:175]
	v_pk_mul_f32 v[62:63], v[62:63], v[150:151]
	v_pk_mul_f32 v[58:59], v[58:59], v[154:155]
	v_pk_mul_f32 v[54:55], v[54:55], v[158:159]
	v_pk_mul_f32 v[50:51], v[50:51], v[172:173]
	v_pk_mul_f32 v[48:49], v[48:49], v[152:153]
	v_pk_mul_f32 v[44:45], v[44:45], v[156:157]
	v_pk_mul_f32 v[40:41], v[40:41], v[160:161]
	v_pk_mul_f32 v[36:37], v[36:37], v[174:175]
	v_pk_mul_f32 v[46:47], v[46:47], v[150:151]
	v_pk_mul_f32 v[42:43], v[42:43], v[154:155]
	v_pk_mul_f32 v[38:39], v[38:39], v[158:159]
	v_pk_mul_f32 v[34:35], v[34:35], v[172:173]
	v_pk_mul_f32 v[32:33], v[32:33], v[152:153]
	v_pk_mul_f32 v[28:29], v[28:29], v[156:157]
	v_pk_mul_f32 v[24:25], v[24:25], v[160:161]
	v_pk_mul_f32 v[20:21], v[20:21], v[174:175]
	v_pk_mul_f32 v[30:31], v[30:31], v[150:151]
	v_pk_mul_f32 v[26:27], v[26:27], v[154:155]
	v_pk_mul_f32 v[22:23], v[22:23], v[158:159]
	v_pk_mul_f32 v[18:19], v[18:19], v[172:173]
	s_branch .LBB0_1303
.Lp5_y2_slow:
	v_max_f32_e32 v76, v206, v76
	v_sub_f32_e32 v77, v206, v76
	v_mul_f32_e32 v77, 0x3e0293ee, v77
	v_exp_f32_e32 v77, v77
	s_nop 0
	v_cndmask_b32_e64 v207, v77, 1.0, s[6:7]
	v_mov_b32_e32 v206, v76
	v_mul_f32_e32 v190, 0xbe0293ee, v76
	s_and_saveexec_b64 s[36:37], s[0:1]
	ds_write_b32 v185, v207 offset:128
	s_or_b64 exec, exec, s[36:37]
	s_waitcnt lgkmcnt(0)
	ds_read_b128 v[78:81], v183 offset:224
	ds_read_b128 v[240:243], v183 offset:192
	ds_read_b128 v[244:247], v183 offset:160
	ds_read_b128 v[248:251], v183 offset:128
	s_waitcnt lgkmcnt(3)
	v_pk_mul_f32 v[16:17], v[16:17], v[80:81]
	s_waitcnt lgkmcnt(2)
	v_pk_mul_f32 v[12:13], v[12:13], v[242:243]
	s_waitcnt lgkmcnt(1)
	v_pk_mul_f32 v[8:9], v[8:9], v[246:247]
	s_waitcnt lgkmcnt(0)
	v_pk_mul_f32 v[4:5], v[4:5], v[250:251]
	v_pk_mul_f32 v[14:15], v[14:15], v[78:79]
	v_pk_mul_f32 v[10:11], v[10:11], v[240:241]
	v_pk_mul_f32 v[6:7], v[6:7], v[244:245]
	v_pk_mul_f32 v[2:3], v[2:3], v[248:249]
	v_pk_mul_f32 v[64:65], v[64:65], v[80:81]
	v_pk_mul_f32 v[60:61], v[60:61], v[242:243]
	v_pk_mul_f32 v[56:57], v[56:57], v[246:247]
	v_pk_mul_f32 v[52:53], v[52:53], v[250:251]
	v_pk_mul_f32 v[62:63], v[62:63], v[78:79]
	v_pk_mul_f32 v[58:59], v[58:59], v[240:241]
	v_pk_mul_f32 v[54:55], v[54:55], v[244:245]
	v_pk_mul_f32 v[50:51], v[50:51], v[248:249]
	v_pk_mul_f32 v[48:49], v[48:49], v[80:81]
	v_pk_mul_f32 v[44:45], v[44:45], v[242:243]
	v_pk_mul_f32 v[40:41], v[40:41], v[246:247]
	v_pk_mul_f32 v[36:37], v[36:37], v[250:251]
	v_pk_mul_f32 v[46:47], v[46:47], v[78:79]
	v_pk_mul_f32 v[42:43], v[42:43], v[240:241]
	v_pk_mul_f32 v[38:39], v[38:39], v[244:245]
	v_pk_mul_f32 v[34:35], v[34:35], v[248:249]
	v_pk_mul_f32 v[32:33], v[32:33], v[80:81]
	v_pk_mul_f32 v[28:29], v[28:29], v[242:243]
	v_pk_mul_f32 v[24:25], v[24:25], v[246:247]
	v_pk_mul_f32 v[20:21], v[20:21], v[250:251]
	v_pk_mul_f32 v[30:31], v[30:31], v[78:79]
	v_pk_mul_f32 v[26:27], v[26:27], v[240:241]
	v_pk_mul_f32 v[22:23], v[22:23], v[244:245]
	v_pk_mul_f32 v[18:19], v[18:19], v[248:249]
	s_branch .LBB0_1311
